# P2 epilogue: f32 residual base loads hoisted, rolling 4-block prefetch with counted vmcnt waits (32 serialized round trips per unit removed)
# speedup vs baseline: 1.0069x; 1.0069x over previous
; __device__ __forceinline__ unsigned pk2(float lo, float hi) { return pg8::cvt_pk_bf16(lo, hi); }
;     __device__ __forceinline__ void operator()(const f32x4 (&acc)[2][2][4][2], const pg8::Unit& u, int wr, int wc, int fr, int fq) const {
;     ...
;                 const int row = row0 + ai * 128 + m * 16; float ss = 0.f;
; #pragma unroll
;                 for (int bj = 0; bj < 2; ++bj) {
;                     const size_t off = (size_t)row * DM + col0 + bj * 128;
;                     float o[8];
;                     if (BASE_BF16) { const u32x4 bw = *(const u32x4*)((const bf16_t*)base + off);
; #pragma unroll
;                         for (int e = 0; e < 4; ++e) { o[2 * e] = __uint_as_float(bw[e] << 16); o[2 * e + 1] = __uint_as_float(bw[e] & 0xffff0000u); } }
;                     else { const f32x4 b0 = *(const f32x4*)((const float*)base + off), b1 = *(const f32x4*)((const float*)base + off + 4);
; #pragma unroll
;                         for (int e = 0; e < 4; ++e) { o[e] = b0[e]; o[4 + e] = b1[e]; } }
; #pragma unroll
;                     for (int n = 0; n < 2; ++n)
; #pragma unroll
;                         for (int e = 0; e < 4; ++e) { const float v = o[4 * n + e] + alpha * acc[ai][bj][m][n][e]; o[4 * n + e] = v; ss += v * v; }
;                     if (OUT_BF16) { u32x4 w; w.x = pk2(o[0], o[1]); w.y = pk2(o[2], o[3]); w.z = pk2(o[4], o[5]); w.w = pk2(o[6], o[7]); *(u32x4*)((bf16_t*)out + off) = w; }
;                     else { *(f32x4*)((float*)out + off) = (f32x4){o[0], o[1], o[2], o[3]}; *(f32x4*)((float*)out + off + 4) = (f32x4){o[4], o[5], o[6], o[7]}; }
;                 }
;                 if (sumsq) { ss += __shfl_xor(ss, 16); ss += __shfl_xor(ss, 32); if (fq == 0) atomicAdd(sumsq + row, ss); }
.LBB0_277:
	v_lshl_add_u32 v152, s56, 8, v158
	v_lshl_or_b32 v156, s57, 8, v160
	v_ashrrev_i32_e32 v153, 31, v152
	v_ashrrev_i32_e32 v157, 31, v156
	v_lshlrev_b64 v[128:129], 10, v[152:153]
	v_lshl_add_u64 v[154:155], v[128:129], 0, v[156:157]
	v_lshl_add_u64 v[168:169], v[154:155], 2, s[12:13]
	s_mov_b64 s[98:99], 0x10000
	s_mov_b64 s[100:101], 0x50000
	v_mov_b32_e32 v232, v168
	v_mov_b32_e32 v233, v169
	global_load_dwordx4 v[174:177], v[232:233], off
	global_load_dwordx4 v[178:181], v[232:233], off offset:16
	global_load_dwordx4 v[182:185], v[232:233], off offset:512
	global_load_dwordx4 v[192:195], v[232:233], off offset:528
	v_lshl_add_u64 v[232:233], v[232:233], 0, s[98:99]
	global_load_dwordx4 v[196:199], v[232:233], off
	global_load_dwordx4 v[200:203], v[232:233], off offset:16
	global_load_dwordx4 v[204:207], v[232:233], off offset:512
	global_load_dwordx4 v[208:211], v[232:233], off offset:528
	v_lshl_add_u64 v[232:233], v[232:233], 0, s[98:99]
	global_load_dwordx4 v[212:215], v[232:233], off
	global_load_dwordx4 v[216:219], v[232:233], off offset:16
	global_load_dwordx4 v[220:223], v[232:233], off offset:512
	global_load_dwordx4 v[224:227], v[232:233], off offset:528
	v_lshl_add_u64 v[232:233], v[232:233], 0, s[98:99]
	global_load_dwordx4 v[228:231], v[232:233], off
	global_load_dwordx4 v[236:239], v[232:233], off offset:16
	global_load_dwordx4 v[240:243], v[232:233], off offset:512
	global_load_dwordx4 v[244:247], v[232:233], off offset:528
	v_lshl_add_u64 v[232:233], v[232:233], 0, s[100:101]
	s_nop 0
	v_readlane_b32 s34, v235, 31
	v_lshlrev_b64 v[170:171], 1, v[154:155]
	v_readlane_b32 s35, v235, 32
	s_andn2_b64 vcc, exec, s[28:29]
	s_waitcnt vmcnt(14)
	v_mov_b32_e32 v132, v174
	v_mov_b32_e32 v133, v175
	v_mov_b32_e32 v134, v176
	v_mov_b32_e32 v135, v177
	v_mov_b32_e32 v128, v178
	v_mov_b32_e32 v129, v179
	v_mov_b32_e32 v130, v180
	v_mov_b32_e32 v131, v181
	v_fma_f32 v165, 0.5, v124, v132
	v_lshl_add_u64 v[172:173], s[34:35], 0, v[170:171]
	v_fma_f32 v166, 0.5, v125, v133
	v_fma_f32 v133, 0.5, v126, v134
	v_fmac_f32_e32 v135, 0.5, v127
	v_fma_f32 v132, 0.5, v120, v128
	v_fma_f32 v129, 0.5, v121, v129
	v_fma_f32 v128, 0.5, v122, v130
	v_fmac_f32_e32 v131, 0.5, v123
	v_cvt_pk_bf16_f32 v120, v165, v166
	v_cvt_pk_bf16_f32 v121, v133, v135
	v_cvt_pk_bf16_f32 v122, v132, v129
	v_cvt_pk_bf16_f32 v123, v128, v131
	global_store_dwordx4 v[172:173], v[120:123], off
	s_nop 0
	s_nop 0
	s_nop 0
	v_cndmask_b32_e64 v130, 0, 1, s[28:29]
	v_or_b32_e32 v170, 0x100, v170
	v_cmp_ne_u32_e64 s[8:9], 1, v130
	v_lshl_add_u64 v[168:169], s[34:35], 0, v[170:171]
	s_waitcnt vmcnt(13)
	v_mov_b32_e32 v124, v182
	v_mov_b32_e32 v125, v183
	v_mov_b32_e32 v126, v184
	v_mov_b32_e32 v127, v185
	v_mov_b32_e32 v120, v192
	v_mov_b32_e32 v121, v193
	v_mov_b32_e32 v122, v194
	v_mov_b32_e32 v123, v195
	v_fma_f32 v130, 0.5, v116, v124
	v_fma_f32 v124, 0.5, v117, v125
	v_fma_f32 v117, 0.5, v118, v126
	v_fmac_f32_e32 v127, 0.5, v119
	s_nop 0
	v_fma_f32 v116, 0.5, v112, v120
	v_fma_f32 v113, 0.5, v113, v121
	v_fma_f32 v112, 0.5, v114, v122
	v_fmac_f32_e32 v123, 0.5, v115
	v_cvt_pk_bf16_f32 v118, v130, v124
	v_cvt_pk_bf16_f32 v119, v117, v127
	v_cvt_pk_bf16_f32 v120, v116, v113
	v_cvt_pk_bf16_f32 v121, v112, v123
	global_store_dwordx4 v[168:169], v[118:121], off
	s_cbranch_vccnz .LBB0_281
	v_mul_f32_e32 v114, v166, v166
	v_fmac_f32_e32 v114, v165, v165
	v_fmac_f32_e32 v114, v133, v133
	v_fmac_f32_e32 v114, v135, v135
	v_fmac_f32_e32 v114, v132, v132
	v_fmac_f32_e32 v114, v129, v129
	v_fmac_f32_e32 v114, v128, v128
	v_fmac_f32_e32 v114, v131, v131
	v_fmac_f32_e32 v114, v130, v130
	v_fmac_f32_e32 v114, v124, v124
	v_fmac_f32_e32 v114, v117, v117
	v_fmac_f32_e32 v114, v127, v127
	v_fmac_f32_e32 v114, v116, v116
	v_fmac_f32_e32 v114, v113, v113
	v_and_b32_e32 v113, 64, v164
	v_fmac_f32_e32 v114, v112, v112
	v_xor_b32_e32 v112, 16, v164
	v_add_u32_e32 v113, 64, v113
	v_cmp_lt_i32_e32 vcc, v112, v113
	v_fmac_f32_e32 v114, v123, v123
	s_nop 0
	v_cndmask_b32_e32 v112, v164, v112, vcc
	v_lshlrev_b32_e32 v112, 2, v112
	ds_bpermute_b32 v112, v112, v114
	s_waitcnt lgkmcnt(0)
	v_add_f32_e32 v112, v114, v112
	v_xor_b32_e32 v114, 32, v164
	v_cmp_lt_i32_e32 vcc, v114, v113
	s_nop 1
	v_cndmask_b32_e32 v113, v164, v114, vcc
	v_lshlrev_b32_e32 v113, 2, v113
	ds_bpermute_b32 v113, v113, v112
	s_and_saveexec_b64 s[34:35], s[4:5]
	s_cbranch_execz .LBB0_280
	v_readlane_b32 s36, v235, 2
	v_readlane_b32 s38, v235, 4
	v_readlane_b32 s39, v235, 5
	s_waitcnt lgkmcnt(0)
	v_add_f32_e32 v112, v112, v113
	v_readlane_b32 s37, v235, 3
	v_lshl_add_u64 v[114:115], v[152:153], 2, s[38:39]
	global_atomic_add_f32 v[114:115], v112, off

; __device__ __forceinline__ unsigned pk2(float lo, float hi) { return pg8::cvt_pk_bf16(lo, hi); }
;     __device__ __forceinline__ void operator()(const f32x4 (&acc)[2][2][4][2], const pg8::Unit& u, int wr, int wc, int fr, int fq) const {
;     ...
;                 const int row = row0 + ai * 128 + m * 16; float ss = 0.f;
; #pragma unroll
;                 for (int bj = 0; bj < 2; ++bj) {
;                     const size_t off = (size_t)row * DM + col0 + bj * 128;
;                     float o[8];
;                     if (BASE_BF16) { const u32x4 bw = *(const u32x4*)((const bf16_t*)base + off);
; #pragma unroll
;                         for (int e = 0; e < 4; ++e) { o[2 * e] = __uint_as_float(bw[e] << 16); o[2 * e + 1] = __uint_as_float(bw[e] & 0xffff0000u); } }
;                     else { const f32x4 b0 = *(const f32x4*)((const float*)base + off), b1 = *(const f32x4*)((const float*)base + off + 4);
; #pragma unroll
;                         for (int e = 0; e < 4; ++e) { o[e] = b0[e]; o[4 + e] = b1[e]; } }
; #pragma unroll
;                     for (int n = 0; n < 2; ++n)
; #pragma unroll
;                         for (int e = 0; e < 4; ++e) { const float v = o[4 * n + e] + alpha * acc[ai][bj][m][n][e]; o[4 * n + e] = v; ss += v * v; }
;                     if (OUT_BF16) { u32x4 w; w.x = pk2(o[0], o[1]); w.y = pk2(o[2], o[3]); w.z = pk2(o[4], o[5]); w.w = pk2(o[6], o[7]); *(u32x4*)((bf16_t*)out + off) = w; }
;                     else { *(f32x4*)((float*)out + off) = (f32x4){o[0], o[1], o[2], o[3]}; *(f32x4*)((float*)out + off + 4) = (f32x4){o[4], o[5], o[6], o[7]}; }
;                 }
;                 if (sumsq) { ss += __shfl_xor(ss, 16); ss += __shfl_xor(ss, 32); if (fq == 0) atomicAdd(sumsq + row, ss); }
.LBB0_281:
	v_or_b32_e32 v112, 16, v152
	s_waitcnt lgkmcnt(0)
	v_ashrrev_i32_e32 v113, 31, v112
	v_lshlrev_b64 v[112:113], 10, v[112:113]
	v_lshl_add_u64 v[120:121], v[112:113], 0, v[156:157]
	v_lshl_add_u64 v[122:123], v[120:121], 2, s[12:13]
	global_load_dwordx4 v[174:177], v[232:233], off
	global_load_dwordx4 v[178:181], v[232:233], off offset:16
	global_load_dwordx4 v[182:185], v[232:233], off offset:512
	global_load_dwordx4 v[192:195], v[232:233], off offset:528
	v_lshl_add_u64 v[232:233], v[232:233], 0, s[98:99]
	s_nop 0
	v_readlane_b32 s34, v235, 31
	v_lshlrev_b64 v[124:125], 1, v[120:121]
	v_readlane_b32 s35, v235, 32
	s_and_b64 vcc, exec, s[8:9]
	s_waitcnt vmcnt(16)
	v_mov_b32_e32 v116, v196
	v_mov_b32_e32 v117, v197
	v_mov_b32_e32 v118, v198
	v_mov_b32_e32 v119, v199
	v_mov_b32_e32 v112, v200
	v_mov_b32_e32 v113, v201
	v_mov_b32_e32 v114, v202
	v_mov_b32_e32 v115, v203
	v_fma_f32 v120, 0.5, v108, v116
	v_lshl_add_u64 v[126:127], s[34:35], 0, v[124:125]
	v_fma_f32 v121, 0.5, v109, v117
	v_fma_f32 v117, 0.5, v110, v118
	v_fmac_f32_e32 v119, 0.5, v111
	s_nop 0
	v_fma_f32 v116, 0.5, v104, v112
	v_fma_f32 v113, 0.5, v105, v113
	v_fma_f32 v112, 0.5, v106, v114
	v_fmac_f32_e32 v115, 0.5, v107
	v_cvt_pk_bf16_f32 v104, v120, v121
	v_cvt_pk_bf16_f32 v105, v117, v119
	v_cvt_pk_bf16_f32 v106, v116, v113
	v_cvt_pk_bf16_f32 v107, v112, v115
	global_store_dwordx4 v[126:127], v[104:107], off
	s_nop 0
	s_nop 0
	s_nop 0
	v_or_b32_e32 v124, 0x100, v124
	v_lshl_add_u64 v[122:123], s[34:35], 0, v[124:125]
	s_waitcnt vmcnt(15)
	v_mov_b32_e32 v108, v204
	v_mov_b32_e32 v109, v205
	v_mov_b32_e32 v110, v206
	v_mov_b32_e32 v111, v207
	v_mov_b32_e32 v104, v208
	v_mov_b32_e32 v105, v209
	v_mov_b32_e32 v106, v210
	v_mov_b32_e32 v107, v211
	v_fma_f32 v114, 0.5, v100, v108
	v_fma_f32 v108, 0.5, v101, v109
	v_fma_f32 v101, 0.5, v102, v110
	v_fmac_f32_e32 v111, 0.5, v103
	s_nop 0
	v_fma_f32 v100, 0.5, v96, v104
	v_fma_f32 v97, 0.5, v97, v105
	v_fma_f32 v96, 0.5, v98, v106
	v_fmac_f32_e32 v107, 0.5, v99
	v_cvt_pk_bf16_f32 v102, v114, v108
	v_cvt_pk_bf16_f32 v103, v101, v111
	v_cvt_pk_bf16_f32 v104, v100, v97
	v_cvt_pk_bf16_f32 v105, v96, v107
	global_store_dwordx4 v[122:123], v[102:105], off
	s_cbranch_vccnz .LBB0_285
	v_mul_f32_e32 v98, v121, v121
	v_fmac_f32_e32 v98, v120, v120
	v_fmac_f32_e32 v98, v117, v117
	v_fmac_f32_e32 v98, v119, v119
	v_fmac_f32_e32 v98, v116, v116
	v_fmac_f32_e32 v98, v113, v113
	v_fmac_f32_e32 v98, v112, v112
	v_fmac_f32_e32 v98, v115, v115
	v_fmac_f32_e32 v98, v114, v114
	v_fmac_f32_e32 v98, v108, v108
	v_fmac_f32_e32 v98, v101, v101
	v_fmac_f32_e32 v98, v111, v111
	v_fmac_f32_e32 v98, v100, v100
	v_fmac_f32_e32 v98, v97, v97
	v_and_b32_e32 v97, 64, v164
	v_fmac_f32_e32 v98, v96, v96
	v_xor_b32_e32 v96, 16, v164
	v_add_u32_e32 v97, 64, v97
	v_cmp_lt_i32_e32 vcc, v96, v97
	v_fmac_f32_e32 v98, v107, v107
	s_nop 0
	v_cndmask_b32_e32 v96, v164, v96, vcc
	v_lshlrev_b32_e32 v96, 2, v96
	ds_bpermute_b32 v96, v96, v98
	s_waitcnt lgkmcnt(0)
	v_add_f32_e32 v96, v98, v96
	v_xor_b32_e32 v98, 32, v164
	v_cmp_lt_i32_e32 vcc, v98, v97
	s_nop 1
	v_cndmask_b32_e32 v97, v164, v98, vcc
	v_lshlrev_b32_e32 v97, 2, v97
	ds_bpermute_b32 v97, v97, v96
	s_and_saveexec_b64 s[34:35], s[4:5]
	s_cbranch_execz .LBB0_284
	v_readlane_b32 s36, v235, 2
	v_readlane_b32 s38, v235, 4
	v_readlane_b32 s39, v235, 5
	s_waitcnt lgkmcnt(0)
	v_add_f32_e32 v96, v96, v97
	v_readlane_b32 s37, v235, 3
	v_lshl_add_u64 v[98:99], v[152:153], 2, s[38:39]
	global_atomic_add_f32 v[98:99], v96, off offset:64

; __device__ __forceinline__ unsigned pk2(float lo, float hi) { return pg8::cvt_pk_bf16(lo, hi); }
;     __device__ __forceinline__ void operator()(const f32x4 (&acc)[2][2][4][2], const pg8::Unit& u, int wr, int wc, int fr, int fq) const {
;     ...
;                 const int row = row0 + ai * 128 + m * 16; float ss = 0.f;
; #pragma unroll
;                 for (int bj = 0; bj < 2; ++bj) {
;                     const size_t off = (size_t)row * DM + col0 + bj * 128;
;                     float o[8];
;                     if (BASE_BF16) { const u32x4 bw = *(const u32x4*)((const bf16_t*)base + off);
; #pragma unroll
;                         for (int e = 0; e < 4; ++e) { o[2 * e] = __uint_as_float(bw[e] << 16); o[2 * e + 1] = __uint_as_float(bw[e] & 0xffff0000u); } }
;                     else { const f32x4 b0 = *(const f32x4*)((const float*)base + off), b1 = *(const f32x4*)((const float*)base + off + 4);
; #pragma unroll
;                         for (int e = 0; e < 4; ++e) { o[e] = b0[e]; o[4 + e] = b1[e]; } }
; #pragma unroll
;                     for (int n = 0; n < 2; ++n)
; #pragma unroll
;                         for (int e = 0; e < 4; ++e) { const float v = o[4 * n + e] + alpha * acc[ai][bj][m][n][e]; o[4 * n + e] = v; ss += v * v; }
;                     if (OUT_BF16) { u32x4 w; w.x = pk2(o[0], o[1]); w.y = pk2(o[2], o[3]); w.z = pk2(o[4], o[5]); w.w = pk2(o[6], o[7]); *(u32x4*)((bf16_t*)out + off) = w; }
;                     else { *(f32x4*)((float*)out + off) = (f32x4){o[0], o[1], o[2], o[3]}; *(f32x4*)((float*)out + off + 4) = (f32x4){o[4], o[5], o[6], o[7]}; }
;                 }
;                 if (sumsq) { ss += __shfl_xor(ss, 16); ss += __shfl_xor(ss, 32); if (fq == 0) atomicAdd(sumsq + row, ss); }
.LBB0_285:
	v_or_b32_e32 v96, 32, v152
	s_waitcnt lgkmcnt(0)
	v_ashrrev_i32_e32 v97, 31, v96
	v_lshlrev_b64 v[96:97], 10, v[96:97]
	v_lshl_add_u64 v[104:105], v[96:97], 0, v[156:157]
	v_lshl_add_u64 v[106:107], v[104:105], 2, s[12:13]
	global_load_dwordx4 v[196:199], v[232:233], off
	global_load_dwordx4 v[200:203], v[232:233], off offset:16
	global_load_dwordx4 v[204:207], v[232:233], off offset:512
	global_load_dwordx4 v[208:211], v[232:233], off offset:528
	v_lshl_add_u64 v[232:233], v[232:233], 0, s[98:99]
	s_nop 0
	v_readlane_b32 s34, v235, 31
	v_lshlrev_b64 v[108:109], 1, v[104:105]
	v_readlane_b32 s35, v235, 32
	s_and_b64 vcc, exec, s[8:9]
	s_waitcnt vmcnt(18)
	v_mov_b32_e32 v100, v212
	v_mov_b32_e32 v101, v213
	v_mov_b32_e32 v102, v214
	v_mov_b32_e32 v103, v215
	v_mov_b32_e32 v96, v216
	v_mov_b32_e32 v97, v217
	v_mov_b32_e32 v98, v218
	v_mov_b32_e32 v99, v219
	v_fma_f32 v104, 0.5, v92, v100
	v_lshl_add_u64 v[110:111], s[34:35], 0, v[108:109]
	v_fma_f32 v105, 0.5, v93, v101
	v_fma_f32 v101, 0.5, v94, v102
	v_fmac_f32_e32 v103, 0.5, v95
	s_nop 0
	v_fma_f32 v100, 0.5, v88, v96
	v_fma_f32 v97, 0.5, v89, v97
	v_fma_f32 v96, 0.5, v90, v98
	v_fmac_f32_e32 v99, 0.5, v91
	v_cvt_pk_bf16_f32 v88, v104, v105
	v_cvt_pk_bf16_f32 v89, v101, v103
	v_cvt_pk_bf16_f32 v90, v100, v97
	v_cvt_pk_bf16_f32 v91, v96, v99
	global_store_dwordx4 v[110:111], v[88:91], off
	s_nop 0
	s_nop 0
	s_nop 0
	v_or_b32_e32 v108, 0x100, v108
	v_lshl_add_u64 v[106:107], s[34:35], 0, v[108:109]
	s_waitcnt vmcnt(17)
	v_mov_b32_e32 v92, v220
	v_mov_b32_e32 v93, v221
	v_mov_b32_e32 v94, v222
	v_mov_b32_e32 v95, v223
	v_mov_b32_e32 v88, v224
	v_mov_b32_e32 v89, v225
	v_mov_b32_e32 v90, v226
	v_mov_b32_e32 v91, v227
	v_fma_f32 v98, 0.5, v84, v92
	v_fma_f32 v92, 0.5, v85, v93
	v_fma_f32 v85, 0.5, v86, v94
	v_fmac_f32_e32 v95, 0.5, v87
	s_nop 0
	v_fma_f32 v84, 0.5, v80, v88
	v_fma_f32 v81, 0.5, v81, v89
	v_fma_f32 v80, 0.5, v82, v90
	v_fmac_f32_e32 v91, 0.5, v83
	v_cvt_pk_bf16_f32 v86, v98, v92
	v_cvt_pk_bf16_f32 v87, v85, v95
	v_cvt_pk_bf16_f32 v88, v84, v81
	v_cvt_pk_bf16_f32 v89, v80, v91
	global_store_dwordx4 v[106:107], v[86:89], off
	s_cbranch_vccnz .LBB0_289
	v_mul_f32_e32 v82, v105, v105
	v_fmac_f32_e32 v82, v104, v104
	v_fmac_f32_e32 v82, v101, v101
	v_fmac_f32_e32 v82, v103, v103
	v_fmac_f32_e32 v82, v100, v100
	v_fmac_f32_e32 v82, v97, v97
	v_fmac_f32_e32 v82, v96, v96
	v_fmac_f32_e32 v82, v99, v99
	v_fmac_f32_e32 v82, v98, v98
	v_fmac_f32_e32 v82, v92, v92
	v_fmac_f32_e32 v82, v85, v85
	v_fmac_f32_e32 v82, v95, v95
	v_fmac_f32_e32 v82, v84, v84
	v_fmac_f32_e32 v82, v81, v81
	v_and_b32_e32 v81, 64, v164
	v_fmac_f32_e32 v82, v80, v80
	v_xor_b32_e32 v80, 16, v164
	v_add_u32_e32 v81, 64, v81
	v_cmp_lt_i32_e32 vcc, v80, v81
	v_fmac_f32_e32 v82, v91, v91
	s_nop 0
	v_cndmask_b32_e32 v80, v164, v80, vcc
	v_lshlrev_b32_e32 v80, 2, v80
	ds_bpermute_b32 v80, v80, v82
	s_waitcnt lgkmcnt(0)
	v_add_f32_e32 v80, v82, v80
	v_xor_b32_e32 v82, 32, v164
	v_cmp_lt_i32_e32 vcc, v82, v81
	s_nop 1
	v_cndmask_b32_e32 v81, v164, v82, vcc
	v_lshlrev_b32_e32 v81, 2, v81
	ds_bpermute_b32 v81, v81, v80
	s_and_saveexec_b64 s[34:35], s[4:5]
	s_cbranch_execz .LBB0_288
	v_readlane_b32 s36, v235, 2
	v_readlane_b32 s38, v235, 4
	v_readlane_b32 s39, v235, 5
	s_waitcnt lgkmcnt(0)
	v_add_f32_e32 v80, v80, v81
	v_readlane_b32 s37, v235, 3
	v_lshl_add_u64 v[82:83], v[152:153], 2, s[38:39]
	global_atomic_add_f32 v[82:83], v80, off offset:128

; __device__ __forceinline__ unsigned pk2(float lo, float hi) { return pg8::cvt_pk_bf16(lo, hi); }
;     __device__ __forceinline__ void operator()(const f32x4 (&acc)[2][2][4][2], const pg8::Unit& u, int wr, int wc, int fr, int fq) const {
;     ...
;                 const int row = row0 + ai * 128 + m * 16; float ss = 0.f;
; #pragma unroll
;                 for (int bj = 0; bj < 2; ++bj) {
;                     const size_t off = (size_t)row * DM + col0 + bj * 128;
;                     float o[8];
;                     if (BASE_BF16) { const u32x4 bw = *(const u32x4*)((const bf16_t*)base + off);
; #pragma unroll
;                         for (int e = 0; e < 4; ++e) { o[2 * e] = __uint_as_float(bw[e] << 16); o[2 * e + 1] = __uint_as_float(bw[e] & 0xffff0000u); } }
;                     else { const f32x4 b0 = *(const f32x4*)((const float*)base + off), b1 = *(const f32x4*)((const float*)base + off + 4);
; #pragma unroll
;                         for (int e = 0; e < 4; ++e) { o[e] = b0[e]; o[4 + e] = b1[e]; } }
; #pragma unroll
;                     for (int n = 0; n < 2; ++n)
; #pragma unroll
;                         for (int e = 0; e < 4; ++e) { const float v = o[4 * n + e] + alpha * acc[ai][bj][m][n][e]; o[4 * n + e] = v; ss += v * v; }
;                     if (OUT_BF16) { u32x4 w; w.x = pk2(o[0], o[1]); w.y = pk2(o[2], o[3]); w.z = pk2(o[4], o[5]); w.w = pk2(o[6], o[7]); *(u32x4*)((bf16_t*)out + off) = w; }
;                     else { *(f32x4*)((float*)out + off) = (f32x4){o[0], o[1], o[2], o[3]}; *(f32x4*)((float*)out + off + 4) = (f32x4){o[4], o[5], o[6], o[7]}; }
;                 }
;                 if (sumsq) { ss += __shfl_xor(ss, 16); ss += __shfl_xor(ss, 32); if (fq == 0) atomicAdd(sumsq + row, ss); }
.LBB0_289:
	v_or_b32_e32 v80, 48, v152
	s_waitcnt lgkmcnt(0)
	v_ashrrev_i32_e32 v81, 31, v80
	v_lshlrev_b64 v[80:81], 10, v[80:81]
	v_lshl_add_u64 v[88:89], v[80:81], 0, v[156:157]
	v_lshl_add_u64 v[90:91], v[88:89], 2, s[12:13]
	global_load_dwordx4 v[212:215], v[232:233], off
	global_load_dwordx4 v[216:219], v[232:233], off offset:16
	global_load_dwordx4 v[220:223], v[232:233], off offset:512
	global_load_dwordx4 v[224:227], v[232:233], off offset:528
	v_lshl_add_u64 v[232:233], v[232:233], 0, s[98:99]
	s_nop 0
	v_readlane_b32 s34, v235, 31
	v_lshlrev_b64 v[92:93], 1, v[88:89]
	v_readlane_b32 s35, v235, 32
	s_and_b64 vcc, exec, s[8:9]
	s_waitcnt vmcnt(20)
	v_mov_b32_e32 v84, v228
	v_mov_b32_e32 v85, v229
	v_mov_b32_e32 v86, v230
	v_mov_b32_e32 v87, v231
	v_mov_b32_e32 v80, v236
	v_mov_b32_e32 v81, v237
	v_mov_b32_e32 v82, v238
	v_mov_b32_e32 v83, v239
	v_fma_f32 v88, 0.5, v76, v84
	v_lshl_add_u64 v[94:95], s[34:35], 0, v[92:93]
	v_fma_f32 v89, 0.5, v77, v85
	v_fma_f32 v85, 0.5, v78, v86
	v_fmac_f32_e32 v87, 0.5, v79
	s_nop 0
	v_fma_f32 v84, 0.5, v72, v80
	v_fma_f32 v81, 0.5, v73, v81
	v_fma_f32 v80, 0.5, v74, v82
	v_fmac_f32_e32 v83, 0.5, v75
	v_cvt_pk_bf16_f32 v72, v88, v89
	v_cvt_pk_bf16_f32 v73, v85, v87
	v_cvt_pk_bf16_f32 v74, v84, v81
	v_cvt_pk_bf16_f32 v75, v80, v83
	global_store_dwordx4 v[94:95], v[72:75], off
	s_nop 0
	s_nop 0
	s_nop 0
	v_or_b32_e32 v92, 0x100, v92
	v_lshl_add_u64 v[90:91], s[34:35], 0, v[92:93]
	s_waitcnt vmcnt(19)
	v_mov_b32_e32 v76, v240
	v_mov_b32_e32 v77, v241
	v_mov_b32_e32 v78, v242
	v_mov_b32_e32 v79, v243
	v_mov_b32_e32 v72, v244
	v_mov_b32_e32 v73, v245
	v_mov_b32_e32 v74, v246
	v_mov_b32_e32 v75, v247
	v_fma_f32 v82, 0.5, v68, v76
	v_fma_f32 v76, 0.5, v69, v77
	v_fma_f32 v69, 0.5, v70, v78
	v_fmac_f32_e32 v79, 0.5, v71
	s_nop 0
	v_fma_f32 v68, 0.5, v64, v72
	v_fma_f32 v65, 0.5, v65, v73
	v_fma_f32 v64, 0.5, v66, v74
	v_fmac_f32_e32 v75, 0.5, v67
	v_cvt_pk_bf16_f32 v70, v82, v76
	v_cvt_pk_bf16_f32 v71, v69, v79
	v_cvt_pk_bf16_f32 v72, v68, v65
	v_cvt_pk_bf16_f32 v73, v64, v75
	global_store_dwordx4 v[90:91], v[70:73], off
	s_cbranch_vccnz .LBB0_293
	v_mul_f32_e32 v66, v89, v89
	v_fmac_f32_e32 v66, v88, v88
	v_fmac_f32_e32 v66, v85, v85
	v_fmac_f32_e32 v66, v87, v87
	v_fmac_f32_e32 v66, v84, v84
	v_fmac_f32_e32 v66, v81, v81
	v_fmac_f32_e32 v66, v80, v80
	v_fmac_f32_e32 v66, v83, v83
	v_fmac_f32_e32 v66, v82, v82
	v_fmac_f32_e32 v66, v76, v76
	v_fmac_f32_e32 v66, v69, v69
	v_fmac_f32_e32 v66, v79, v79
	v_fmac_f32_e32 v66, v68, v68
	v_fmac_f32_e32 v66, v65, v65
	v_and_b32_e32 v65, 64, v164
	v_fmac_f32_e32 v66, v64, v64
	v_xor_b32_e32 v64, 16, v164
	v_add_u32_e32 v65, 64, v65
	v_cmp_lt_i32_e32 vcc, v64, v65
	v_fmac_f32_e32 v66, v75, v75
	s_nop 0
	v_cndmask_b32_e32 v64, v164, v64, vcc
	v_lshlrev_b32_e32 v64, 2, v64
	ds_bpermute_b32 v64, v64, v66
	s_waitcnt lgkmcnt(0)
	v_add_f32_e32 v64, v66, v64
	v_xor_b32_e32 v66, 32, v164
	v_cmp_lt_i32_e32 vcc, v66, v65
	s_nop 1
	v_cndmask_b32_e32 v65, v164, v66, vcc
	v_lshlrev_b32_e32 v65, 2, v65
	ds_bpermute_b32 v65, v65, v64
	s_and_saveexec_b64 s[34:35], s[4:5]
	s_cbranch_execz .LBB0_292
	v_readlane_b32 s36, v235, 2
	v_readlane_b32 s38, v235, 4
	v_readlane_b32 s39, v235, 5
	s_waitcnt lgkmcnt(0)
	v_add_f32_e32 v64, v64, v65
	v_readlane_b32 s37, v235, 3
	v_lshl_add_u64 v[66:67], v[152:153], 2, s[38:39]
	global_atomic_add_f32 v[66:67], v64, off offset:192

; __device__ __forceinline__ unsigned pk2(float lo, float hi) { return pg8::cvt_pk_bf16(lo, hi); }
;     __device__ __forceinline__ void operator()(const f32x4 (&acc)[2][2][4][2], const pg8::Unit& u, int wr, int wc, int fr, int fq) const {
;     ...
;                 const int row = row0 + ai * 128 + m * 16; float ss = 0.f;
; #pragma unroll
;                 for (int bj = 0; bj < 2; ++bj) {
;                     const size_t off = (size_t)row * DM + col0 + bj * 128;
;                     float o[8];
;                     if (BASE_BF16) { const u32x4 bw = *(const u32x4*)((const bf16_t*)base + off);
; #pragma unroll
;                         for (int e = 0; e < 4; ++e) { o[2 * e] = __uint_as_float(bw[e] << 16); o[2 * e + 1] = __uint_as_float(bw[e] & 0xffff0000u); } }
;                     else { const f32x4 b0 = *(const f32x4*)((const float*)base + off), b1 = *(const f32x4*)((const float*)base + off + 4);
; #pragma unroll
;                         for (int e = 0; e < 4; ++e) { o[e] = b0[e]; o[4 + e] = b1[e]; } }
; #pragma unroll
;                     for (int n = 0; n < 2; ++n)
; #pragma unroll
;                         for (int e = 0; e < 4; ++e) { const float v = o[4 * n + e] + alpha * acc[ai][bj][m][n][e]; o[4 * n + e] = v; ss += v * v; }
;                     if (OUT_BF16) { u32x4 w; w.x = pk2(o[0], o[1]); w.y = pk2(o[2], o[3]); w.z = pk2(o[4], o[5]); w.w = pk2(o[6], o[7]); *(u32x4*)((bf16_t*)out + off) = w; }
;                     else { *(f32x4*)((float*)out + off) = (f32x4){o[0], o[1], o[2], o[3]}; *(f32x4*)((float*)out + off + 4) = (f32x4){o[4], o[5], o[6], o[7]}; }
;                 }
;                 if (sumsq) { ss += __shfl_xor(ss, 16); ss += __shfl_xor(ss, 32); if (fq == 0) atomicAdd(sumsq + row, ss); }
.LBB0_293:
	s_nop 0
	v_lshl_add_u64 v[72:73], v[154:155], 0, s[18:19]
	v_lshl_add_u64 v[74:75], v[72:73], 2, s[12:13]
	global_load_dwordx4 v[228:231], v[232:233], off
	global_load_dwordx4 v[236:239], v[232:233], off offset:16
	global_load_dwordx4 v[240:243], v[232:233], off offset:512
	global_load_dwordx4 v[244:247], v[232:233], off offset:528
	s_waitcnt lgkmcnt(0)
	s_nop 0
	v_readlane_b32 s34, v235, 31
	v_lshlrev_b64 v[76:77], 1, v[72:73]
	v_readlane_b32 s35, v235, 32
	s_and_b64 vcc, exec, s[8:9]
	s_waitcnt vmcnt(20)
	v_mov_b32_e32 v68, v174
	v_mov_b32_e32 v69, v175
	v_mov_b32_e32 v70, v176
	v_mov_b32_e32 v71, v177
	v_mov_b32_e32 v64, v178
	v_mov_b32_e32 v65, v179
	v_mov_b32_e32 v66, v180
	v_mov_b32_e32 v67, v181
	v_fma_f32 v72, 0.5, v60, v68
	v_lshl_add_u64 v[78:79], s[34:35], 0, v[76:77]
	v_fma_f32 v73, 0.5, v61, v69
	v_fma_f32 v69, 0.5, v62, v70
	v_fmac_f32_e32 v71, 0.5, v63
	s_nop 0
	v_fma_f32 v68, 0.5, v56, v64
	v_fma_f32 v65, 0.5, v57, v65
	v_fma_f32 v64, 0.5, v58, v66
	v_fmac_f32_e32 v67, 0.5, v59
	v_cvt_pk_bf16_f32 v56, v72, v73
	v_cvt_pk_bf16_f32 v57, v69, v71
	v_cvt_pk_bf16_f32 v58, v68, v65
	v_cvt_pk_bf16_f32 v59, v64, v67
	global_store_dwordx4 v[78:79], v[56:59], off
	s_nop 0
	s_nop 0
	s_nop 0
	v_or_b32_e32 v76, 0x100, v76
	v_lshl_add_u64 v[74:75], s[34:35], 0, v[76:77]
	s_waitcnt vmcnt(19)
	v_mov_b32_e32 v60, v182
	v_mov_b32_e32 v61, v183
	v_mov_b32_e32 v62, v184
	v_mov_b32_e32 v63, v185
	v_mov_b32_e32 v56, v192
	v_mov_b32_e32 v57, v193
	v_mov_b32_e32 v58, v194
	v_mov_b32_e32 v59, v195
	v_fma_f32 v66, 0.5, v52, v60
	v_fma_f32 v60, 0.5, v53, v61
	v_fma_f32 v53, 0.5, v54, v62
	v_fmac_f32_e32 v63, 0.5, v55
	s_nop 0
	v_fma_f32 v52, 0.5, v48, v56
	v_fma_f32 v49, 0.5, v49, v57
	v_fma_f32 v48, 0.5, v50, v58
	v_fmac_f32_e32 v59, 0.5, v51
	v_cvt_pk_bf16_f32 v54, v66, v60
	v_cvt_pk_bf16_f32 v55, v53, v63
	v_cvt_pk_bf16_f32 v56, v52, v49
	v_cvt_pk_bf16_f32 v57, v48, v59
	global_store_dwordx4 v[74:75], v[54:57], off
	s_cbranch_vccnz .LBB0_297
	v_mul_f32_e32 v50, v73, v73
	v_fmac_f32_e32 v50, v72, v72
	v_fmac_f32_e32 v50, v69, v69
	v_fmac_f32_e32 v50, v71, v71
	v_fmac_f32_e32 v50, v68, v68
	v_fmac_f32_e32 v50, v65, v65
	v_fmac_f32_e32 v50, v64, v64
	v_fmac_f32_e32 v50, v67, v67
	v_fmac_f32_e32 v50, v66, v66
	v_fmac_f32_e32 v50, v60, v60
	v_fmac_f32_e32 v50, v53, v53
	v_fmac_f32_e32 v50, v63, v63
	v_fmac_f32_e32 v50, v52, v52
	v_fmac_f32_e32 v50, v49, v49
	v_and_b32_e32 v49, 64, v164
	v_fmac_f32_e32 v50, v48, v48
	v_xor_b32_e32 v48, 16, v164
	v_add_u32_e32 v49, 64, v49
	v_cmp_lt_i32_e32 vcc, v48, v49
	v_fmac_f32_e32 v50, v59, v59
	s_nop 0
	v_cndmask_b32_e32 v48, v164, v48, vcc
	v_lshlrev_b32_e32 v48, 2, v48
	ds_bpermute_b32 v48, v48, v50
	s_waitcnt lgkmcnt(0)
	v_add_f32_e32 v48, v50, v48
	v_xor_b32_e32 v50, 32, v164
	v_cmp_lt_i32_e32 vcc, v50, v49
	s_nop 1
	v_cndmask_b32_e32 v49, v164, v50, vcc
	v_lshlrev_b32_e32 v49, 2, v49
	ds_bpermute_b32 v49, v49, v48
	s_and_saveexec_b64 s[34:35], s[4:5]
	s_cbranch_execz .LBB0_296
	v_readlane_b32 s36, v235, 2
	v_readlane_b32 s38, v235, 4
	v_readlane_b32 s39, v235, 5
	s_waitcnt lgkmcnt(0)
	v_add_f32_e32 v48, v48, v49
	v_readlane_b32 s37, v235, 3
	v_lshl_add_u64 v[50:51], v[152:153], 2, s[38:39]
	global_atomic_add_f32 v[50:51], v48, off offset:512

; __device__ __forceinline__ unsigned pk2(float lo, float hi) { return pg8::cvt_pk_bf16(lo, hi); }
;     __device__ __forceinline__ void operator()(const f32x4 (&acc)[2][2][4][2], const pg8::Unit& u, int wr, int wc, int fr, int fq) const {
;     ...
;                 const int row = row0 + ai * 128 + m * 16; float ss = 0.f;
; #pragma unroll
;                 for (int bj = 0; bj < 2; ++bj) {
;                     const size_t off = (size_t)row * DM + col0 + bj * 128;
;                     float o[8];
;                     if (BASE_BF16) { const u32x4 bw = *(const u32x4*)((const bf16_t*)base + off);
; #pragma unroll
;                         for (int e = 0; e < 4; ++e) { o[2 * e] = __uint_as_float(bw[e] << 16); o[2 * e + 1] = __uint_as_float(bw[e] & 0xffff0000u); } }
;                     else { const f32x4 b0 = *(const f32x4*)((const float*)base + off), b1 = *(const f32x4*)((const float*)base + off + 4);
; #pragma unroll
;                         for (int e = 0; e < 4; ++e) { o[e] = b0[e]; o[4 + e] = b1[e]; } }
; #pragma unroll
;                     for (int n = 0; n < 2; ++n)
; #pragma unroll
;                         for (int e = 0; e < 4; ++e) { const float v = o[4 * n + e] + alpha * acc[ai][bj][m][n][e]; o[4 * n + e] = v; ss += v * v; }
;                     if (OUT_BF16) { u32x4 w; w.x = pk2(o[0], o[1]); w.y = pk2(o[2], o[3]); w.z = pk2(o[4], o[5]); w.w = pk2(o[6], o[7]); *(u32x4*)((bf16_t*)out + off) = w; }
;                     else { *(f32x4*)((float*)out + off) = (f32x4){o[0], o[1], o[2], o[3]}; *(f32x4*)((float*)out + off + 4) = (f32x4){o[4], o[5], o[6], o[7]}; }
;                 }
;                 if (sumsq) { ss += __shfl_xor(ss, 16); ss += __shfl_xor(ss, 32); if (fq == 0) atomicAdd(sumsq + row, ss); }
.LBB0_297:
	s_nop 0
	v_lshl_add_u64 v[56:57], v[154:155], 0, s[20:21]
	v_lshl_add_u64 v[58:59], v[56:57], 2, s[12:13]
	s_nop 0
	s_waitcnt lgkmcnt(0)
	s_nop 0
	v_readlane_b32 s34, v235, 31
	v_lshlrev_b64 v[60:61], 1, v[56:57]
	v_readlane_b32 s35, v235, 32
	s_and_b64 vcc, exec, s[8:9]
	s_waitcnt vmcnt(16)
	v_mov_b32_e32 v52, v196
	v_mov_b32_e32 v53, v197
	v_mov_b32_e32 v54, v198
	v_mov_b32_e32 v55, v199
	v_mov_b32_e32 v48, v200
	v_mov_b32_e32 v49, v201
	v_mov_b32_e32 v50, v202
	v_mov_b32_e32 v51, v203
	v_fma_f32 v56, 0.5, v44, v52
	v_lshl_add_u64 v[62:63], s[34:35], 0, v[60:61]
	v_fma_f32 v57, 0.5, v45, v53
	v_fma_f32 v53, 0.5, v46, v54
	v_fmac_f32_e32 v55, 0.5, v47
	s_nop 0
	v_fma_f32 v52, 0.5, v40, v48
	v_fma_f32 v49, 0.5, v41, v49
	v_fma_f32 v48, 0.5, v42, v50
	v_fmac_f32_e32 v51, 0.5, v43
	v_cvt_pk_bf16_f32 v40, v56, v57
	v_cvt_pk_bf16_f32 v41, v53, v55
	v_cvt_pk_bf16_f32 v42, v52, v49
	v_cvt_pk_bf16_f32 v43, v48, v51
	global_store_dwordx4 v[62:63], v[40:43], off
	s_nop 0
	s_nop 0
	s_nop 0
	v_or_b32_e32 v60, 0x100, v60
	v_lshl_add_u64 v[58:59], s[34:35], 0, v[60:61]
	s_waitcnt vmcnt(15)
	v_mov_b32_e32 v44, v204
	v_mov_b32_e32 v45, v205
	v_mov_b32_e32 v46, v206
	v_mov_b32_e32 v47, v207
	v_mov_b32_e32 v40, v208
	v_mov_b32_e32 v41, v209
	v_mov_b32_e32 v42, v210
	v_mov_b32_e32 v43, v211
	v_fma_f32 v50, 0.5, v36, v44
	v_fma_f32 v44, 0.5, v37, v45
	v_fma_f32 v37, 0.5, v38, v46
	v_fmac_f32_e32 v47, 0.5, v39
	s_nop 0
	v_fma_f32 v36, 0.5, v32, v40
	v_fma_f32 v33, 0.5, v33, v41
	v_fma_f32 v32, 0.5, v34, v42
	v_fmac_f32_e32 v43, 0.5, v35
	v_cvt_pk_bf16_f32 v38, v50, v44
	v_cvt_pk_bf16_f32 v39, v37, v47
	v_cvt_pk_bf16_f32 v40, v36, v33
	v_cvt_pk_bf16_f32 v41, v32, v43
	global_store_dwordx4 v[58:59], v[38:41], off
	s_cbranch_vccnz .LBB0_301
	v_mul_f32_e32 v34, v57, v57
	v_fmac_f32_e32 v34, v56, v56
	v_fmac_f32_e32 v34, v53, v53
	v_fmac_f32_e32 v34, v55, v55
	v_fmac_f32_e32 v34, v52, v52
	v_fmac_f32_e32 v34, v49, v49
	v_fmac_f32_e32 v34, v48, v48
	v_fmac_f32_e32 v34, v51, v51
	v_fmac_f32_e32 v34, v50, v50
	v_fmac_f32_e32 v34, v44, v44
	v_fmac_f32_e32 v34, v37, v37
	v_fmac_f32_e32 v34, v47, v47
	v_fmac_f32_e32 v34, v36, v36
	v_fmac_f32_e32 v34, v33, v33
	v_and_b32_e32 v33, 64, v164
	v_fmac_f32_e32 v34, v32, v32
	v_xor_b32_e32 v32, 16, v164
	v_add_u32_e32 v33, 64, v33
	v_cmp_lt_i32_e32 vcc, v32, v33
	v_fmac_f32_e32 v34, v43, v43
	s_nop 0
	v_cndmask_b32_e32 v32, v164, v32, vcc
	v_lshlrev_b32_e32 v32, 2, v32
	ds_bpermute_b32 v32, v32, v34
	s_waitcnt lgkmcnt(0)
	v_add_f32_e32 v32, v34, v32
	v_xor_b32_e32 v34, 32, v164
	v_cmp_lt_i32_e32 vcc, v34, v33
	s_nop 1
	v_cndmask_b32_e32 v33, v164, v34, vcc
	v_lshlrev_b32_e32 v33, 2, v33
	ds_bpermute_b32 v33, v33, v32
	s_and_saveexec_b64 s[34:35], s[4:5]
	s_cbranch_execz .LBB0_300
	v_readlane_b32 s36, v235, 2
	v_readlane_b32 s38, v235, 4
	v_readlane_b32 s39, v235, 5
	s_waitcnt lgkmcnt(0)
	v_add_f32_e32 v32, v32, v33
	v_readlane_b32 s37, v235, 3
	v_lshl_add_u64 v[34:35], v[152:153], 2, s[38:39]
	global_atomic_add_f32 v[34:35], v32, off offset:576

; __device__ __forceinline__ unsigned pk2(float lo, float hi) { return pg8::cvt_pk_bf16(lo, hi); }
;     __device__ __forceinline__ void operator()(const f32x4 (&acc)[2][2][4][2], const pg8::Unit& u, int wr, int wc, int fr, int fq) const {
;     ...
;                 const int row = row0 + ai * 128 + m * 16; float ss = 0.f;
; #pragma unroll
;                 for (int bj = 0; bj < 2; ++bj) {
;                     const size_t off = (size_t)row * DM + col0 + bj * 128;
;                     float o[8];
;                     if (BASE_BF16) { const u32x4 bw = *(const u32x4*)((const bf16_t*)base + off);
; #pragma unroll
;                         for (int e = 0; e < 4; ++e) { o[2 * e] = __uint_as_float(bw[e] << 16); o[2 * e + 1] = __uint_as_float(bw[e] & 0xffff0000u); } }
;                     else { const f32x4 b0 = *(const f32x4*)((const float*)base + off), b1 = *(const f32x4*)((const float*)base + off + 4);
; #pragma unroll
;                         for (int e = 0; e < 4; ++e) { o[e] = b0[e]; o[4 + e] = b1[e]; } }
; #pragma unroll
;                     for (int n = 0; n < 2; ++n)
; #pragma unroll
;                         for (int e = 0; e < 4; ++e) { const float v = o[4 * n + e] + alpha * acc[ai][bj][m][n][e]; o[4 * n + e] = v; ss += v * v; }
;                     if (OUT_BF16) { u32x4 w; w.x = pk2(o[0], o[1]); w.y = pk2(o[2], o[3]); w.z = pk2(o[4], o[5]); w.w = pk2(o[6], o[7]); *(u32x4*)((bf16_t*)out + off) = w; }
;                     else { *(f32x4*)((float*)out + off) = (f32x4){o[0], o[1], o[2], o[3]}; *(f32x4*)((float*)out + off + 4) = (f32x4){o[4], o[5], o[6], o[7]}; }
;                 }
;                 if (sumsq) { ss += __shfl_xor(ss, 16); ss += __shfl_xor(ss, 32); if (fq == 0) atomicAdd(sumsq + row, ss); }
.LBB0_301:
	s_nop 0
	v_lshl_add_u64 v[40:41], v[154:155], 0, s[22:23]
	v_lshl_add_u64 v[42:43], v[40:41], 2, s[12:13]
	s_nop 0
	s_waitcnt lgkmcnt(0)
	s_nop 0
	v_readlane_b32 s34, v235, 31
	v_lshlrev_b64 v[44:45], 1, v[40:41]
	v_readlane_b32 s35, v235, 32
	s_and_b64 vcc, exec, s[8:9]
	s_waitcnt vmcnt(12)
	v_mov_b32_e32 v36, v212
	v_mov_b32_e32 v37, v213
	v_mov_b32_e32 v38, v214
	v_mov_b32_e32 v39, v215
	v_mov_b32_e32 v32, v216
	v_mov_b32_e32 v33, v217
	v_mov_b32_e32 v34, v218
	v_mov_b32_e32 v35, v219
	v_fma_f32 v40, 0.5, v28, v36
	v_lshl_add_u64 v[46:47], s[34:35], 0, v[44:45]
	v_fma_f32 v41, 0.5, v29, v37
	v_fma_f32 v37, 0.5, v30, v38
	v_fmac_f32_e32 v39, 0.5, v31
	s_nop 0
	v_fma_f32 v36, 0.5, v24, v32
	v_fma_f32 v33, 0.5, v25, v33
	v_fma_f32 v32, 0.5, v26, v34
	v_fmac_f32_e32 v35, 0.5, v27
	v_cvt_pk_bf16_f32 v24, v40, v41
	v_cvt_pk_bf16_f32 v25, v37, v39
	v_cvt_pk_bf16_f32 v26, v36, v33
	v_cvt_pk_bf16_f32 v27, v32, v35
	global_store_dwordx4 v[46:47], v[24:27], off
	s_nop 0
	s_nop 0
	s_nop 0
	v_or_b32_e32 v44, 0x100, v44
	v_lshl_add_u64 v[42:43], s[34:35], 0, v[44:45]
	s_waitcnt vmcnt(11)
	v_mov_b32_e32 v28, v220
	v_mov_b32_e32 v29, v221
	v_mov_b32_e32 v30, v222
	v_mov_b32_e32 v31, v223
	v_mov_b32_e32 v24, v224
	v_mov_b32_e32 v25, v225
	v_mov_b32_e32 v26, v226
	v_mov_b32_e32 v27, v227
	v_fma_f32 v34, 0.5, v20, v28
	v_fma_f32 v28, 0.5, v21, v29
	v_fma_f32 v21, 0.5, v22, v30
	v_fmac_f32_e32 v31, 0.5, v23
	s_nop 0
	v_fma_f32 v20, 0.5, v16, v24
	v_fma_f32 v17, 0.5, v17, v25
	v_fma_f32 v16, 0.5, v18, v26
	v_fmac_f32_e32 v27, 0.5, v19
	v_cvt_pk_bf16_f32 v22, v34, v28
	v_cvt_pk_bf16_f32 v23, v21, v31
	v_cvt_pk_bf16_f32 v24, v20, v17
	v_cvt_pk_bf16_f32 v25, v16, v27
	global_store_dwordx4 v[42:43], v[22:25], off
	s_cbranch_vccnz .LBB0_305
	v_mul_f32_e32 v18, v41, v41
	v_fmac_f32_e32 v18, v40, v40
	v_fmac_f32_e32 v18, v37, v37
	v_fmac_f32_e32 v18, v39, v39
	v_fmac_f32_e32 v18, v36, v36
	v_fmac_f32_e32 v18, v33, v33
	v_fmac_f32_e32 v18, v32, v32
	v_fmac_f32_e32 v18, v35, v35
	v_fmac_f32_e32 v18, v34, v34
	v_fmac_f32_e32 v18, v28, v28
	v_fmac_f32_e32 v18, v21, v21
	v_fmac_f32_e32 v18, v31, v31
	v_fmac_f32_e32 v18, v20, v20
	v_fmac_f32_e32 v18, v17, v17
	v_and_b32_e32 v17, 64, v164
	v_fmac_f32_e32 v18, v16, v16
	v_xor_b32_e32 v16, 16, v164
	v_add_u32_e32 v17, 64, v17
	v_cmp_lt_i32_e32 vcc, v16, v17
	v_fmac_f32_e32 v18, v27, v27
	s_nop 0
	v_cndmask_b32_e32 v16, v164, v16, vcc
	v_lshlrev_b32_e32 v16, 2, v16
	ds_bpermute_b32 v16, v16, v18
	s_waitcnt lgkmcnt(0)
	v_add_f32_e32 v16, v18, v16
	v_xor_b32_e32 v18, 32, v164
	v_cmp_lt_i32_e32 vcc, v18, v17
	s_nop 1
	v_cndmask_b32_e32 v17, v164, v18, vcc
	v_lshlrev_b32_e32 v17, 2, v17
	ds_bpermute_b32 v17, v17, v16
	s_and_saveexec_b64 s[34:35], s[4:5]
	s_cbranch_execz .LBB0_304
	v_readlane_b32 s36, v235, 2
	v_readlane_b32 s38, v235, 4
	v_readlane_b32 s39, v235, 5
	s_waitcnt lgkmcnt(0)
	v_add_f32_e32 v16, v16, v17
	v_readlane_b32 s37, v235, 3
	v_lshl_add_u64 v[18:19], v[152:153], 2, s[38:39]
	global_atomic_add_f32 v[18:19], v16, off offset:640

; __device__ __forceinline__ unsigned pk2(float lo, float hi) { return pg8::cvt_pk_bf16(lo, hi); }
;     __device__ __forceinline__ void operator()(const f32x4 (&acc)[2][2][4][2], const pg8::Unit& u, int wr, int wc, int fr, int fq) const {
;     ...
;                 const int row = row0 + ai * 128 + m * 16; float ss = 0.f;
; #pragma unroll
;                 for (int bj = 0; bj < 2; ++bj) {
;                     const size_t off = (size_t)row * DM + col0 + bj * 128;
;                     float o[8];
;                     if (BASE_BF16) { const u32x4 bw = *(const u32x4*)((const bf16_t*)base + off);
; #pragma unroll
;                         for (int e = 0; e < 4; ++e) { o[2 * e] = __uint_as_float(bw[e] << 16); o[2 * e + 1] = __uint_as_float(bw[e] & 0xffff0000u); } }
;                     else { const f32x4 b0 = *(const f32x4*)((const float*)base + off), b1 = *(const f32x4*)((const float*)base + off + 4);
; #pragma unroll
;                         for (int e = 0; e < 4; ++e) { o[e] = b0[e]; o[4 + e] = b1[e]; } }
; #pragma unroll
;                     for (int n = 0; n < 2; ++n)
; #pragma unroll
;                         for (int e = 0; e < 4; ++e) { const float v = o[4 * n + e] + alpha * acc[ai][bj][m][n][e]; o[4 * n + e] = v; ss += v * v; }
;                     if (OUT_BF16) { u32x4 w; w.x = pk2(o[0], o[1]); w.y = pk2(o[2], o[3]); w.z = pk2(o[4], o[5]); w.w = pk2(o[6], o[7]); *(u32x4*)((bf16_t*)out + off) = w; }
;                     else { *(f32x4*)((float*)out + off) = (f32x4){o[0], o[1], o[2], o[3]}; *(f32x4*)((float*)out + off + 4) = (f32x4){o[4], o[5], o[6], o[7]}; }
;                 }
;                 if (sumsq) { ss += __shfl_xor(ss, 16); ss += __shfl_xor(ss, 32); if (fq == 0) atomicAdd(sumsq + row, ss); }
.LBB0_305:
	s_nop 0
	v_lshl_add_u64 v[24:25], v[154:155], 0, s[24:25]
	v_lshl_add_u64 v[26:27], v[24:25], 2, s[12:13]
	s_nop 0
	s_waitcnt lgkmcnt(0)
	s_nop 0
	v_readlane_b32 s34, v235, 31
	v_lshlrev_b64 v[28:29], 1, v[24:25]
	v_readlane_b32 s35, v235, 32
	s_and_b64 vcc, exec, s[8:9]
	s_waitcnt vmcnt(8)
	v_mov_b32_e32 v20, v228
	v_mov_b32_e32 v21, v229
	v_mov_b32_e32 v22, v230
	v_mov_b32_e32 v23, v231
	v_mov_b32_e32 v16, v236
	v_mov_b32_e32 v17, v237
	v_mov_b32_e32 v18, v238
	v_mov_b32_e32 v19, v239
	v_fma_f32 v24, 0.5, v12, v20
	v_lshl_add_u64 v[30:31], s[34:35], 0, v[28:29]
	v_fma_f32 v25, 0.5, v13, v21
	v_fma_f32 v21, 0.5, v14, v22
	v_fmac_f32_e32 v23, 0.5, v15
	s_nop 0
	v_fma_f32 v20, 0.5, v8, v16
	v_fma_f32 v17, 0.5, v9, v17
	v_fma_f32 v16, 0.5, v10, v18
	v_fmac_f32_e32 v19, 0.5, v11
	v_cvt_pk_bf16_f32 v8, v24, v25
	v_cvt_pk_bf16_f32 v9, v21, v23
	v_cvt_pk_bf16_f32 v10, v20, v17
	v_cvt_pk_bf16_f32 v11, v16, v19
	global_store_dwordx4 v[30:31], v[8:11], off
	s_nop 0
	s_nop 0
	s_nop 0
	v_or_b32_e32 v28, 0x100, v28
	v_lshl_add_u64 v[26:27], s[34:35], 0, v[28:29]
	s_waitcnt vmcnt(7)
	v_mov_b32_e32 v12, v240
	v_mov_b32_e32 v13, v241
	v_mov_b32_e32 v14, v242
	v_mov_b32_e32 v15, v243
	v_mov_b32_e32 v8, v244
	v_mov_b32_e32 v9, v245
	v_mov_b32_e32 v10, v246
	v_mov_b32_e32 v11, v247
	v_fma_f32 v18, 0.5, v4, v12
	v_fma_f32 v12, 0.5, v5, v13
	v_fma_f32 v5, 0.5, v6, v14
	v_fmac_f32_e32 v15, 0.5, v7
	s_nop 0
	v_fma_f32 v4, 0.5, v0, v8
	v_fma_f32 v1, 0.5, v1, v9
	v_fma_f32 v0, 0.5, v2, v10
	v_fmac_f32_e32 v11, 0.5, v3
	v_cvt_pk_bf16_f32 v6, v18, v12
	v_cvt_pk_bf16_f32 v7, v5, v15
	v_cvt_pk_bf16_f32 v8, v4, v1
	v_cvt_pk_bf16_f32 v9, v0, v11
	global_store_dwordx4 v[26:27], v[6:9], off
	s_cbranch_vccnz .LBB0_309
	v_mul_f32_e32 v2, v25, v25
	v_fmac_f32_e32 v2, v24, v24
	v_fmac_f32_e32 v2, v21, v21
	v_fmac_f32_e32 v2, v23, v23
	v_fmac_f32_e32 v2, v20, v20
	v_fmac_f32_e32 v2, v17, v17
	v_fmac_f32_e32 v2, v16, v16
	v_fmac_f32_e32 v2, v19, v19
	v_fmac_f32_e32 v2, v18, v18
	v_fmac_f32_e32 v2, v12, v12
	v_fmac_f32_e32 v2, v5, v5
	v_fmac_f32_e32 v2, v15, v15
	v_fmac_f32_e32 v2, v4, v4
	v_fmac_f32_e32 v2, v1, v1
	v_and_b32_e32 v1, 64, v164
	v_fmac_f32_e32 v2, v0, v0
	v_xor_b32_e32 v0, 16, v164
	v_add_u32_e32 v1, 64, v1
	v_cmp_lt_i32_e32 vcc, v0, v1
	v_fmac_f32_e32 v2, v11, v11
	s_nop 0
	v_cndmask_b32_e32 v0, v164, v0, vcc
	v_lshlrev_b32_e32 v0, 2, v0
	ds_bpermute_b32 v0, v0, v2
	s_waitcnt lgkmcnt(0)
	v_add_f32_e32 v0, v2, v0
	v_xor_b32_e32 v2, 32, v164
	v_cmp_lt_i32_e32 vcc, v2, v1
	s_nop 1
	v_cndmask_b32_e32 v1, v164, v2, vcc
	v_lshlrev_b32_e32 v1, 2, v1
	ds_bpermute_b32 v1, v1, v0
	s_and_saveexec_b64 s[8:9], s[4:5]
	s_cbranch_execz .LBB0_308
	v_readlane_b32 s36, v235, 2
	v_readlane_b32 s38, v235, 4
	v_readlane_b32 s39, v235, 5
	s_waitcnt lgkmcnt(0)
	v_add_f32_e32 v0, v0, v1
	v_readlane_b32 s37, v235, 3
	v_lshl_add_u64 v[2:3], v[152:153], 2, s[38:39]
	global_atomic_add_f32 v[2:3], v0, off offset:704
